# hand-written exact final top-256 selection: linear-bin histogram, second-level histogram inside the threshold bin, remaining ties dropped through a 32-bit in-bin composite; compiled exact code kept as
# speedup vs baseline: 1.0912x; 1.0012x over previous
.Lpr_w11:
	s_mov_b64 exec, s[22:23]
	s_bitcmp1_b32 s16, 31
	s_cselect_b32 s17, 0x80000000, -1
	s_xor_b32 s17, s16, s17
	s_mov_b64 exec, s[58:59]
	v_mov_b32_e32 v40, s11
	v_mov_b32_e32 v92, s19
	ds_write_b32 v40, v92
	v_mov_b32_e32 v93, s17
	ds_write_b32 v40, v93 offset:128
	s_mov_b64 exec, s[22:23]
	s_branch .LBB0_143

.LBB0_223:
	v_or_b32_e32 v9, s54, v143
	v_lshl_add_u32 v23, v9, 2, 0
	v_add_u32_e32 v15, 0x24000, v23
	ds_read_b32 v8, v15
	s_movk_i32 s2, 0x100
	s_waitcnt lgkmcnt(0)
	v_cmp_lt_i32_e32 vcc, s2, v8
	s_and_saveexec_b64 s[2:3], vcc
	s_cbranch_execz .LBB0_222
	v_readfirstlane_b32 s8, v9
	v_readfirstlane_b32 s24, v143
	s_mul_i32 s9, s8, 0xc00
	s_mul_i32 s10, s8, 0x600
	s_add_i32 s10, s10, 0x18000
	s_lshl_b32 s11, s8, 2
	s_add_i32 s11, s11, 0x24000
	v_mov_b32_e32 v40, s11
	ds_read_b32 v92, v40
	s_waitcnt lgkmcnt(0)
	v_readfirstlane_b32 s12, v92
	s_add_i32 s13, s12, -1
	v_min_u32_e32 v93, s13, v190
	v_lshl_add_u32 v94, v93, 2, s9
	v_lshl_add_u32 v93, v93, 1, s10
	ds_read_b32 v161, v94
	ds_read_u16 v142, v93
	v_min_u32_e32 v95, s13, v185
	v_lshl_add_u32 v120, v95, 2, s9
	v_lshl_add_u32 v95, v95, 1, s10
	ds_read_b32 v162, v120
	ds_read_u16 v143, v95
	v_min_u32_e32 v93, s13, v192
	v_lshl_add_u32 v94, v93, 2, s9
	v_lshl_add_u32 v93, v93, 1, s10
	ds_read_b32 v163, v94
	ds_read_u16 v144, v93
	v_min_u32_e32 v95, s13, v191
	v_lshl_add_u32 v120, v95, 2, s9
	v_lshl_add_u32 v95, v95, 1, s10
	ds_read_b32 v164, v120
	ds_read_u16 v145, v95
	v_min_u32_e32 v93, s13, v0
	v_lshl_add_u32 v94, v93, 2, s9
	v_lshl_add_u32 v93, v93, 1, s10
	ds_read_b32 v165, v94
	ds_read_u16 v146, v93
	v_min_u32_e32 v95, s13, v1
	v_lshl_add_u32 v120, v95, 2, s9
	v_lshl_add_u32 v95, v95, 1, s10
	ds_read_b32 v166, v120
	ds_read_u16 v148, v95
	v_min_u32_e32 v93, s13, v2
	v_lshl_add_u32 v94, v93, 2, s9
	v_lshl_add_u32 v93, v93, 1, s10
	ds_read_b32 v167, v94
	ds_read_u16 v149, v93
	v_min_u32_e32 v95, s13, v3
	v_lshl_add_u32 v120, v95, 2, s9
	v_lshl_add_u32 v95, v95, 1, s10
	ds_read_b32 v168, v120
	ds_read_u16 v150, v95
	v_min_u32_e32 v93, s13, v6
	v_lshl_add_u32 v94, v93, 2, s9
	v_lshl_add_u32 v93, v93, 1, s10
	ds_read_b32 v169, v94
	ds_read_u16 v152, v93
	v_min_u32_e32 v95, s13, v7
	v_lshl_add_u32 v120, v95, 2, s9
	v_lshl_add_u32 v95, v95, 1, s10
	ds_read_b32 v170, v120
	ds_read_u16 v153, v95
	v_min_u32_e32 v93, s13, v4
	v_lshl_add_u32 v94, v93, 2, s9
	v_lshl_add_u32 v93, v93, 1, s10
	ds_read_b32 v171, v94
	ds_read_u16 v159, v93
	v_min_u32_e32 v95, s13, v5
	v_lshl_add_u32 v120, v95, 2, s9
	v_lshl_add_u32 v95, v95, 1, s10
	ds_read_b32 v172, v120
	ds_read_u16 v160, v95
	ds_write_b128 v127, a[206:209]
	s_waitcnt lgkmcnt(1)
	v_ashrrev_i32_e32 v93, 31, v161
	v_or_b32_e32 v93, 0x80000000, v93
	v_xor_b32_e32 v108, v161, v93
	v_ashrrev_i32_e32 v94, 31, v162
	v_or_b32_e32 v94, 0x80000000, v94
	v_xor_b32_e32 v109, v162, v94
	v_ashrrev_i32_e32 v93, 31, v163
	v_or_b32_e32 v93, 0x80000000, v93
	v_xor_b32_e32 v110, v163, v93
	v_ashrrev_i32_e32 v94, 31, v164
	v_or_b32_e32 v94, 0x80000000, v94
	v_xor_b32_e32 v111, v164, v94
	v_ashrrev_i32_e32 v93, 31, v165
	v_or_b32_e32 v93, 0x80000000, v93
	v_xor_b32_e32 v112, v165, v93
	v_ashrrev_i32_e32 v94, 31, v166
	v_or_b32_e32 v94, 0x80000000, v94
	v_xor_b32_e32 v113, v166, v94
	v_ashrrev_i32_e32 v93, 31, v167
	v_or_b32_e32 v93, 0x80000000, v93
	v_xor_b32_e32 v114, v167, v93
	v_ashrrev_i32_e32 v94, 31, v168
	v_or_b32_e32 v94, 0x80000000, v94
	v_xor_b32_e32 v115, v168, v94
	v_ashrrev_i32_e32 v93, 31, v169
	v_or_b32_e32 v93, 0x80000000, v93
	v_xor_b32_e32 v116, v169, v93
	v_ashrrev_i32_e32 v94, 31, v170
	v_or_b32_e32 v94, 0x80000000, v94
	v_xor_b32_e32 v117, v170, v94
	v_ashrrev_i32_e32 v93, 31, v171
	v_or_b32_e32 v93, 0x80000000, v93
	v_xor_b32_e32 v118, v171, v93
	v_ashrrev_i32_e32 v94, 31, v172
	v_or_b32_e32 v94, 0x80000000, v94
	v_xor_b32_e32 v119, v172, v94
	v_max3_u32 v92, v108, v109, v110
	v_min3_u32 v93, v108, v109, v110
	v_max3_u32 v92, v111, v112, v92
	v_min3_u32 v93, v111, v112, v93
	v_max3_u32 v92, v113, v114, v92
	v_min3_u32 v93, v113, v114, v93
	v_max3_u32 v92, v115, v116, v92
	v_min3_u32 v93, v115, v116, v93
	v_max3_u32 v92, v117, v118, v92
	v_min3_u32 v93, v117, v118, v93
	v_max_u32_e32 v92, v119, v92
	v_min_u32_e32 v93, v119, v93
	s_nop 0
	v_max_u32_dpp v92, v92, v92 quad_perm:[1,0,3,2] row_mask:0xf bank_mask:0xf bound_ctrl:1
	v_min_u32_dpp v93, v93, v93 quad_perm:[1,0,3,2] row_mask:0xf bank_mask:0xf bound_ctrl:1
	s_nop 0
	v_max_u32_dpp v92, v92, v92 quad_perm:[2,3,0,1] row_mask:0xf bank_mask:0xf bound_ctrl:1
	v_min_u32_dpp v93, v93, v93 quad_perm:[2,3,0,1] row_mask:0xf bank_mask:0xf bound_ctrl:1
	s_nop 0
	v_max_u32_dpp v92, v92, v92 row_half_mirror row_mask:0xf bank_mask:0xf bound_ctrl:1
	v_min_u32_dpp v93, v93, v93 row_half_mirror row_mask:0xf bank_mask:0xf bound_ctrl:1
	s_nop 0
	v_max_u32_dpp v92, v92, v92 row_mirror row_mask:0xf bank_mask:0xf bound_ctrl:1
	v_min_u32_dpp v93, v93, v93 row_mirror row_mask:0xf bank_mask:0xf bound_ctrl:1
	s_nop 1
	v_readlane_b32 s15, v92, 0
	v_readlane_b32 s16, v92, 16
	v_readlane_b32 s17, v92, 32
	v_readlane_b32 s18, v92, 48
	s_max_u32 s15, s15, s16
	s_max_u32 s17, s17, s18
	s_max_u32 s15, s15, s17
	v_readlane_b32 s16, v93, 0
	v_readlane_b32 s17, v93, 16
	v_readlane_b32 s18, v93, 32
	v_readlane_b32 s19, v93, 48
	s_min_u32 s16, s16, s17
	s_min_u32 s18, s18, s19
	s_min_u32 s16, s16, s18
	s_sub_u32 s17, s15, 0x3000000
	s_cselect_b32 s17, 0, s17
	s_max_u32 s14, s16, s17
	s_sub_u32 s16, s15, s14
	s_add_u32 s16, s16, 1
	s_cmpk_le_u32 s16, 0x100
	s_cbranch_scc1 .Lfn_orig
	v_mov_b32_e32 v92, s16
	v_cvt_f32_u32_e32 v92, v92
	v_rcp_f32_e32 v92, v92
	s_nop 0
	v_mul_f32_e32 v92, 0x53800000, v92
	v_cvt_u32_f32_e32 v92, v92
	s_nop 0
	v_readfirstlane_b32 s21, v92
	s_nop 1
	v_max_u32_e32 v93, s14, v108
	v_subrev_u32_e32 v93, s14, v93
	v_mul_hi_u32 v93, v93, s21
	v_min_u32_e32 v173, 0xff, v93
	v_max_u32_e32 v94, s14, v109
	v_subrev_u32_e32 v94, s14, v94
	v_mul_hi_u32 v94, v94, s21
	v_min_u32_e32 v174, 0xff, v94
	v_max_u32_e32 v95, s14, v110
	v_subrev_u32_e32 v95, s14, v95
	v_mul_hi_u32 v95, v95, s21
	v_min_u32_e32 v175, 0xff, v95
	v_max_u32_e32 v93, s14, v111
	v_subrev_u32_e32 v93, s14, v93
	v_mul_hi_u32 v93, v93, s21
	v_min_u32_e32 v176, 0xff, v93
	v_max_u32_e32 v94, s14, v112
	v_subrev_u32_e32 v94, s14, v94
	v_mul_hi_u32 v94, v94, s21
	v_min_u32_e32 v177, 0xff, v94
	v_max_u32_e32 v95, s14, v113
	v_subrev_u32_e32 v95, s14, v95
	v_mul_hi_u32 v95, v95, s21
	v_min_u32_e32 v178, 0xff, v95
	v_max_u32_e32 v93, s14, v114
	v_subrev_u32_e32 v93, s14, v93
	v_mul_hi_u32 v93, v93, s21
	v_min_u32_e32 v179, 0xff, v93
	v_max_u32_e32 v94, s14, v115
	v_subrev_u32_e32 v94, s14, v94
	v_mul_hi_u32 v94, v94, s21
	v_min_u32_e32 v180, 0xff, v94
	v_max_u32_e32 v95, s14, v116
	v_subrev_u32_e32 v95, s14, v95
	v_mul_hi_u32 v95, v95, s21
	v_min_u32_e32 v181, 0xff, v95
	v_max_u32_e32 v93, s14, v117
	v_subrev_u32_e32 v93, s14, v93
	v_mul_hi_u32 v93, v93, s21
	v_min_u32_e32 v182, 0xff, v93
	v_max_u32_e32 v94, s14, v118
	v_subrev_u32_e32 v94, s14, v94
	v_mul_hi_u32 v94, v94, s21
	v_min_u32_e32 v183, 0xff, v94
	v_max_u32_e32 v95, s14, v119
	v_subrev_u32_e32 v95, s14, v95
	v_mul_hi_u32 v95, v95, s21
	v_min_u32_e32 v184, 0xff, v95
	v_cmp_gt_u32_e64 s[26:27], s12, v190
	v_cmp_gt_u32_e64 s[28:29], s12, v185
	v_cmp_gt_u32_e64 s[30:31], s12, v192
	v_cndmask_b32_e64 v173, 0, v173, s[26:27]
	v_cmp_gt_u32_e64 s[26:27], s12, v191
	v_cndmask_b32_e64 v174, 0, v174, s[28:29]
	v_cmp_gt_u32_e64 s[28:29], s12, v0
	v_cndmask_b32_e64 v175, 0, v175, s[30:31]
	v_cmp_gt_u32_e64 s[30:31], s12, v1
	v_cndmask_b32_e64 v176, 0, v176, s[26:27]
	v_cmp_gt_u32_e64 s[26:27], s12, v2
	v_cndmask_b32_e64 v177, 0, v177, s[28:29]
	v_cmp_gt_u32_e64 s[28:29], s12, v3
	v_cndmask_b32_e64 v178, 0, v178, s[30:31]
	v_cmp_gt_u32_e64 s[30:31], s12, v6
	v_cndmask_b32_e64 v179, 0, v179, s[26:27]
	v_cmp_gt_u32_e64 s[26:27], s12, v7
	v_cndmask_b32_e64 v180, 0, v180, s[28:29]
	v_cmp_gt_u32_e64 s[28:29], s12, v4
	v_cndmask_b32_e64 v181, 0, v181, s[30:31]
	v_cmp_gt_u32_e64 s[30:31], s12, v5
	v_cndmask_b32_e64 v182, 0, v182, s[26:27]
	s_nop 0
	v_cndmask_b32_e64 v183, 0, v183, s[28:29]
	v_cndmask_b32_e64 v184, 0, v184, s[30:31]
	s_mov_b64 s[22:23], exec
	v_cmp_ne_u32_e64 s[26:27], 0, v173
	v_lshl_add_u32 v93, v173, 2, v121
	s_mov_b64 exec, s[26:27]
	ds_add_u32 v93, v252
	s_mov_b64 exec, s[22:23]
	v_cmp_ne_u32_e64 s[28:29], 0, v174
	v_lshl_add_u32 v94, v174, 2, v121
	s_mov_b64 exec, s[28:29]
	ds_add_u32 v94, v252
	s_mov_b64 exec, s[22:23]
	v_cmp_ne_u32_e64 s[30:31], 0, v175
	v_lshl_add_u32 v95, v175, 2, v121
	s_mov_b64 exec, s[30:31]
	ds_add_u32 v95, v252
	s_mov_b64 exec, s[22:23]
	v_cmp_ne_u32_e64 s[26:27], 0, v176
	v_lshl_add_u32 v93, v176, 2, v121
	s_mov_b64 exec, s[26:27]
	ds_add_u32 v93, v252
	s_mov_b64 exec, s[22:23]
	v_cmp_ne_u32_e64 s[28:29], 0, v177
	v_lshl_add_u32 v94, v177, 2, v121
	s_mov_b64 exec, s[28:29]
	ds_add_u32 v94, v252
	s_mov_b64 exec, s[22:23]
	v_cmp_ne_u32_e64 s[30:31], 0, v178
	v_lshl_add_u32 v95, v178, 2, v121
	s_mov_b64 exec, s[30:31]
	ds_add_u32 v95, v252
	s_mov_b64 exec, s[22:23]
	v_cmp_ne_u32_e64 s[26:27], 0, v179
	v_lshl_add_u32 v93, v179, 2, v121
	s_mov_b64 exec, s[26:27]
	ds_add_u32 v93, v252
	s_mov_b64 exec, s[22:23]
	v_cmp_ne_u32_e64 s[28:29], 0, v180
	v_lshl_add_u32 v94, v180, 2, v121
	s_mov_b64 exec, s[28:29]
	ds_add_u32 v94, v252
	s_mov_b64 exec, s[22:23]
	v_cmp_ne_u32_e64 s[30:31], 0, v181
	v_lshl_add_u32 v95, v181, 2, v121
	s_mov_b64 exec, s[30:31]
	ds_add_u32 v95, v252
	s_mov_b64 exec, s[22:23]
	v_cmp_ne_u32_e64 s[26:27], 0, v182
	v_lshl_add_u32 v93, v182, 2, v121
	s_mov_b64 exec, s[26:27]
	ds_add_u32 v93, v252
	s_mov_b64 exec, s[22:23]
	v_cmp_ne_u32_e64 s[28:29], 0, v183
	v_lshl_add_u32 v94, v183, 2, v121
	s_mov_b64 exec, s[28:29]
	ds_add_u32 v94, v252
	s_mov_b64 exec, s[22:23]
	v_cmp_ne_u32_e64 s[30:31], 0, v184
	v_lshl_add_u32 v95, v184, 2, v121
	s_mov_b64 exec, s[30:31]
	ds_add_u32 v95, v252
	s_mov_b64 exec, s[22:23]
	ds_read_b128 v[92:95], v127
	s_waitcnt lgkmcnt(0)
	v_add_u32_e32 v120, v92, v93
	v_add3_u32 v120, v120, v94, v95
	v_mov_b32_e32 v122, v120
	s_nop 1
	v_add_u32_dpp v122, v122, v122 row_shr:1 row_mask:0xf bank_mask:0xf bound_ctrl:1
	s_nop 1
	v_add_u32_dpp v122, v122, v122 row_shr:2 row_mask:0xf bank_mask:0xf bound_ctrl:1
	s_nop 1
	v_add_u32_dpp v122, v122, v122 row_shr:4 row_mask:0xf bank_mask:0xf bound_ctrl:1
	s_nop 1
	v_add_u32_dpp v122, v122, v122 row_shr:8 row_mask:0xf bank_mask:0xf bound_ctrl:1
	s_nop 1
	v_add_u32_dpp v122, v122, v122 row_bcast:15 row_mask:0xa bank_mask:0xf
	s_nop 1
	v_add_u32_dpp v122, v122, v122 row_bcast:31 row_mask:0xc bank_mask:0xf
	s_nop 1
	v_readlane_b32 s16, v122, 63
	s_nop 1
	v_sub_u32_e32 v123, s16, v122
	v_add_u32_e32 v124, v123, v95
	v_add_u32_e32 v126, v124, v94
	v_add_u32_e32 v128, v126, v93
	v_add_u32_e32 v129, v128, v92
	s_movk_i32 s17, 0x100
	v_lshlrev_b32_e32 v130, 2, v190
	v_cmp_le_u32_e64 s[26:27], s17, v128
	v_cmp_le_u32_e64 s[28:29], s17, v126
	v_cmp_le_u32_e64 s[30:31], s17, v124
	v_mov_b32_e32 v134, v130
	v_or_b32_e32 v131, 1, v134
	v_cndmask_b32_e64 v129, v129, v128, s[26:27]
	v_cndmask_b32_e64 v130, v130, v131, s[26:27]
	v_or_b32_e32 v131, 2, v134
	v_cndmask_b32_e64 v129, v129, v126, s[28:29]
	v_cndmask_b32_e64 v130, v130, v131, s[28:29]
	v_or_b32_e32 v131, 3, v134
	v_cndmask_b32_e64 v129, v129, v124, s[30:31]
	v_cndmask_b32_e64 v130, v130, v131, s[30:31]
	v_add_u32_e32 v132, v123, v120
	v_cmp_gt_u32_e64 s[26:27], s17, v123
	v_cmp_le_u32_e64 s[28:29], s17, v132
	s_nop 0
	s_and_b64 s[26:27], s[26:27], s[28:29]
	s_cmp_eq_u64 s[26:27], 0
	s_cbranch_scc1 .Lfn_orig
	s_ff1_i32_b64 s18, s[26:27]
	s_nop 3
	v_readlane_b32 s19, v129, s18
	v_readlane_b32 s20, v130, s18
	s_cmp_eq_u32 s20, 0
	s_cbranch_scc1 .Lfn_orig
	v_mov_b32_e32 v92, s21
	v_cvt_f32_u32_e32 v92, v92
	v_rcp_f32_e32 v92, v92
	v_mov_b32_e32 v93, s20
	v_cvt_f32_u32_e32 v93, v93
	v_mul_f32_e32 v92, 0x4f800000, v92
	v_mul_f32_e32 v92, v92, v93
	v_mul_f32_e32 v92, 0x3f7ffff0, v92
	v_cvt_u32_f32_e32 v92, v92
	s_nop 0
	v_readfirstlane_b32 s16, v92
	s_add_u32 s16, s16, s14
	s_mov_b32 s13, s16
	v_mov_b32_e32 v136, 0
	v_cmp_eq_u32_e64 s[26:27], s20, v173
	v_cmp_eq_u32_e64 s[28:29], s20, v174
	v_cmp_eq_u32_e64 s[30:31], s20, v175
	v_addc_co_u32_e64 v136, vcc, 0, v136, s[26:27]
	v_cmp_eq_u32_e64 s[26:27], s20, v176
	v_addc_co_u32_e64 v136, vcc, 0, v136, s[28:29]
	v_cmp_eq_u32_e64 s[28:29], s20, v177
	v_addc_co_u32_e64 v136, vcc, 0, v136, s[30:31]
	v_cmp_eq_u32_e64 s[30:31], s20, v178
	v_addc_co_u32_e64 v136, vcc, 0, v136, s[26:27]
	v_cmp_eq_u32_e64 s[26:27], s20, v179
	v_addc_co_u32_e64 v136, vcc, 0, v136, s[28:29]
	v_cmp_eq_u32_e64 s[28:29], s20, v180
	v_addc_co_u32_e64 v136, vcc, 0, v136, s[30:31]
	v_cmp_eq_u32_e64 s[30:31], s20, v181
	v_addc_co_u32_e64 v136, vcc, 0, v136, s[26:27]
	v_cmp_eq_u32_e64 s[26:27], s20, v182
	v_addc_co_u32_e64 v136, vcc, 0, v136, s[28:29]
	v_cmp_eq_u32_e64 s[28:29], s20, v183
	v_addc_co_u32_e64 v136, vcc, 0, v136, s[30:31]
	v_cmp_eq_u32_e64 s[30:31], s20, v184
	v_addc_co_u32_e64 v136, vcc, 0, v136, s[26:27]
	s_nop 0
	v_addc_co_u32_e64 v136, vcc, 0, v136, s[28:29]
	v_addc_co_u32_e64 v136, vcc, 0, v136, s[30:31]
	s_nop 1
	v_add_u32_dpp v136, v136, v136 quad_perm:[1,0,3,2] row_mask:0xf bank_mask:0xf bound_ctrl:1
	s_nop 1
	v_add_u32_dpp v136, v136, v136 quad_perm:[2,3,0,1] row_mask:0xf bank_mask:0xf bound_ctrl:1
	s_nop 1
	v_add_u32_dpp v136, v136, v136 row_half_mirror row_mask:0xf bank_mask:0xf bound_ctrl:1
	s_nop 1
	v_add_u32_dpp v136, v136, v136 row_mirror row_mask:0xf bank_mask:0xf bound_ctrl:1
	s_nop 1
	v_readlane_b32 s14, v136, 0
	v_readlane_b32 s15, v136, 16
	v_readlane_b32 s17, v136, 32
	v_readlane_b32 s18, v136, 48
	s_add_i32 s14, s14, s15
	s_add_i32 s17, s17, s18
	s_add_i32 s14, s14, s17
	s_sub_i32 s15, s19, s14
	s_sub_i32 s15, 0x100, s15
	s_sub_i32 s25, s14, s15
	s_cmp_eq_u32 s25, 0
	s_cbranch_scc1 .Lfn_nodrop
	s_cmpk_le_u32 s25, 3
	s_cbranch_scc1 .Lfn_direct
	v_mov_b32_e32 v92, s21
	v_cvt_f32_u32_e32 v92, v92
	v_rcp_f32_e32 v92, v92
	s_nop 0
	v_mul_f32_e32 v92, 0x4f800000, v92
	v_mul_f32_e32 v92, 0x3f800008, v92
	v_cvt_u32_f32_e32 v92, v92
	v_add_u32_e32 v92, 0x40, v92
	v_cvt_f32_u32_e32 v93, v92
	v_rcp_f32_e32 v93, v93
	s_nop 0
	v_mul_f32_e32 v93, 0x53800000, v93
	v_cvt_u32_f32_e32 v93, v93
	s_nop 0
	v_readfirstlane_b32 s17, v92
	v_readfirstlane_b32 s18, v93
	s_cmpk_le_u32 s17, 0x100
	s_cbranch_scc1 .Lfn_orig
	ds_write_b128 v127, a[206:209]
	s_mov_b64 s[22:23], exec
	v_cmp_eq_u32_e64 s[26:27], s20, v173
	v_subrev_u32_e32 v93, s13, v108
	v_mul_hi_u32 v93, v93, s18
	v_min_u32_e32 v120, 0xff, v93
	v_lshl_add_u32 v93, v120, 2, v121
	s_mov_b64 exec, s[26:27]
	ds_add_u32 v93, v252
	s_mov_b64 exec, s[22:23]
	v_cmp_eq_u32_e64 s[28:29], s20, v174
	v_subrev_u32_e32 v94, s13, v109
	v_mul_hi_u32 v94, v94, s18
	v_min_u32_e32 v122, 0xff, v94
	v_lshl_add_u32 v94, v122, 2, v121
	s_mov_b64 exec, s[28:29]
	ds_add_u32 v94, v252
	s_mov_b64 exec, s[22:23]
	v_cmp_eq_u32_e64 s[30:31], s20, v175
	v_subrev_u32_e32 v95, s13, v110
	v_mul_hi_u32 v95, v95, s18
	v_min_u32_e32 v123, 0xff, v95
	v_lshl_add_u32 v95, v123, 2, v121
	s_mov_b64 exec, s[30:31]
	ds_add_u32 v95, v252
	s_mov_b64 exec, s[22:23]
	v_cmp_eq_u32_e64 s[26:27], s20, v176
	v_subrev_u32_e32 v93, s13, v111
	v_mul_hi_u32 v93, v93, s18
	v_min_u32_e32 v124, 0xff, v93
	v_lshl_add_u32 v93, v124, 2, v121
	s_mov_b64 exec, s[26:27]
	ds_add_u32 v93, v252
	s_mov_b64 exec, s[22:23]
	v_cmp_eq_u32_e64 s[28:29], s20, v177
	v_subrev_u32_e32 v94, s13, v112
	v_mul_hi_u32 v94, v94, s18
	v_min_u32_e32 v126, 0xff, v94
	v_lshl_add_u32 v94, v126, 2, v121
	s_mov_b64 exec, s[28:29]
	ds_add_u32 v94, v252
	s_mov_b64 exec, s[22:23]
	v_cmp_eq_u32_e64 s[30:31], s20, v178
	v_subrev_u32_e32 v95, s13, v113
	v_mul_hi_u32 v95, v95, s18
	v_min_u32_e32 v128, 0xff, v95
	v_lshl_add_u32 v95, v128, 2, v121
	s_mov_b64 exec, s[30:31]
	ds_add_u32 v95, v252
	s_mov_b64 exec, s[22:23]
	v_cmp_eq_u32_e64 s[26:27], s20, v179
	v_subrev_u32_e32 v93, s13, v114
	v_mul_hi_u32 v93, v93, s18
	v_min_u32_e32 v129, 0xff, v93
	v_lshl_add_u32 v93, v129, 2, v121
	s_mov_b64 exec, s[26:27]
	ds_add_u32 v93, v252
	s_mov_b64 exec, s[22:23]
	v_cmp_eq_u32_e64 s[28:29], s20, v180
	v_subrev_u32_e32 v94, s13, v115
	v_mul_hi_u32 v94, v94, s18
	v_min_u32_e32 v130, 0xff, v94
	v_lshl_add_u32 v94, v130, 2, v121
	s_mov_b64 exec, s[28:29]
	ds_add_u32 v94, v252
	s_mov_b64 exec, s[22:23]
	v_cmp_eq_u32_e64 s[30:31], s20, v181
	v_subrev_u32_e32 v95, s13, v116
	v_mul_hi_u32 v95, v95, s18
	v_min_u32_e32 v131, 0xff, v95
	v_lshl_add_u32 v95, v131, 2, v121
	s_mov_b64 exec, s[30:31]
	ds_add_u32 v95, v252
	s_mov_b64 exec, s[22:23]
	v_cmp_eq_u32_e64 s[26:27], s20, v182
	v_subrev_u32_e32 v93, s13, v117
	v_mul_hi_u32 v93, v93, s18
	v_min_u32_e32 v132, 0xff, v93
	v_lshl_add_u32 v93, v132, 2, v121
	s_mov_b64 exec, s[26:27]
	ds_add_u32 v93, v252
	s_mov_b64 exec, s[22:23]
	v_cmp_eq_u32_e64 s[28:29], s20, v183
	v_subrev_u32_e32 v94, s13, v118
	v_mul_hi_u32 v94, v94, s18
	v_min_u32_e32 v134, 0xff, v94
	v_lshl_add_u32 v94, v134, 2, v121
	s_mov_b64 exec, s[28:29]
	ds_add_u32 v94, v252
	s_mov_b64 exec, s[22:23]
	v_cmp_eq_u32_e64 s[30:31], s20, v184
	v_subrev_u32_e32 v95, s13, v119
	v_mul_hi_u32 v95, v95, s18
	v_min_u32_e32 v135, 0xff, v95
	v_lshl_add_u32 v95, v135, 2, v121
	s_mov_b64 exec, s[30:31]
	ds_add_u32 v95, v252
	s_mov_b64 exec, s[22:23]
	ds_read_b128 v[92:95], v127
	s_waitcnt lgkmcnt(0)
	v_add_u32_e32 v136, v92, v93
	v_add3_u32 v136, v136, v94, v95
	v_mov_b32_e32 v137, v136
	s_nop 1
	v_add_u32_dpp v137, v137, v137 row_shr:1 row_mask:0xf bank_mask:0xf bound_ctrl:1
	s_nop 1
	v_add_u32_dpp v137, v137, v137 row_shr:2 row_mask:0xf bank_mask:0xf bound_ctrl:1
	s_nop 1
	v_add_u32_dpp v137, v137, v137 row_shr:4 row_mask:0xf bank_mask:0xf bound_ctrl:1
	s_nop 1
	v_add_u32_dpp v137, v137, v137 row_shr:8 row_mask:0xf bank_mask:0xf bound_ctrl:1
	s_nop 1
	v_add_u32_dpp v137, v137, v137 row_bcast:15 row_mask:0xa bank_mask:0xf
	s_nop 1
	v_add_u32_dpp v137, v137, v137 row_bcast:31 row_mask:0xc bank_mask:0xf
	s_nop 1
	v_readlane_b32 s17, v137, 63
	s_nop 1
	v_sub_u32_e32 v138, s17, v137
	v_add_u32_e32 v140, v138, v95
	v_add_u32_e32 v95, v140, v94
	v_add_u32_e32 v94, v95, v93
	v_add_u32_e32 v93, v94, v92
	v_lshlrev_b32_e32 v92, 2, v190
	v_cmp_le_u32_e64 s[26:27], s15, v94
	v_cmp_le_u32_e64 s[28:29], s15, v95
	v_cmp_le_u32_e64 s[30:31], s15, v140
	v_mov_b32_e32 v137, v92
	v_mov_b32_e32 v136, v93
	v_or_b32_e32 v93, 1, v137
	v_cndmask_b32_e64 v136, v136, v94, s[26:27]
	v_cndmask_b32_e64 v92, v92, v93, s[26:27]
	v_or_b32_e32 v93, 2, v137
	v_cndmask_b32_e64 v136, v136, v95, s[28:29]
	v_cndmask_b32_e64 v92, v92, v93, s[28:29]
	v_or_b32_e32 v93, 3, v137
	v_cndmask_b32_e64 v136, v136, v140, s[30:31]
	v_cndmask_b32_e64 v92, v92, v93, s[30:31]
	v_add_u32_e32 v94, v138, v95
	v_cmp_gt_u32_e64 s[26:27], s15, v138
	v_cmp_le_u32_e64 s[28:29], s15, v136
	s_nop 0
	s_and_b64 s[26:27], s[26:27], s[28:29]
	s_cmp_eq_u64 s[26:27], 0
	s_cbranch_scc1 .Lfn_orig
	s_ff1_i32_b64 s17, s[26:27]
	s_nop 3
	v_readlane_b32 s25, v136, s17
	v_readlane_b32 s14, v92, s17
	s_sub_i32 s25, s25, s15
	s_cmpk_gt_u32 s25, 4
	s_cbranch_scc1 .Lfn_orig
	v_cmp_eq_u32_e64 s[26:27], s20, v173
	v_cmp_gt_u32_e64 s[28:29], s14, v120
	v_cmp_eq_u32_e64 s[30:31], s14, v120
	v_subrev_u32_e32 v93, s13, v108
	v_sub_u32_e32 v94, 0x3fff, v142
	s_and_b64 s[28:29], s[28:29], s[26:27]
	s_and_b64 s[30:31], s[30:31], s[26:27]
	v_lshl_or_b32 v93, v93, 14, v94
	s_nop 1
	v_cndmask_b32_e64 v173, v173, 0, s[28:29]
	v_cndmask_b32_e64 v120, -1, v93, s[30:31]
	v_cmp_eq_u32_e64 s[26:27], s20, v174
	v_cmp_gt_u32_e64 s[28:29], s14, v122
	v_cmp_eq_u32_e64 s[30:31], s14, v122
	v_subrev_u32_e32 v93, s13, v109
	v_sub_u32_e32 v94, 0x3fff, v143
	s_and_b64 s[28:29], s[28:29], s[26:27]
	s_and_b64 s[30:31], s[30:31], s[26:27]
	v_lshl_or_b32 v93, v93, 14, v94
	s_nop 1
	v_cndmask_b32_e64 v174, v174, 0, s[28:29]
	v_cndmask_b32_e64 v122, -1, v93, s[30:31]
	v_cmp_eq_u32_e64 s[26:27], s20, v175
	v_cmp_gt_u32_e64 s[28:29], s14, v123
	v_cmp_eq_u32_e64 s[30:31], s14, v123
	v_subrev_u32_e32 v93, s13, v110
	v_sub_u32_e32 v94, 0x3fff, v144
	s_and_b64 s[28:29], s[28:29], s[26:27]
	s_and_b64 s[30:31], s[30:31], s[26:27]
	v_lshl_or_b32 v93, v93, 14, v94
	s_nop 1
	v_cndmask_b32_e64 v175, v175, 0, s[28:29]
	v_cndmask_b32_e64 v123, -1, v93, s[30:31]
	v_cmp_eq_u32_e64 s[26:27], s20, v176
	v_cmp_gt_u32_e64 s[28:29], s14, v124
	v_cmp_eq_u32_e64 s[30:31], s14, v124
	v_subrev_u32_e32 v93, s13, v111
	v_sub_u32_e32 v94, 0x3fff, v145
	s_and_b64 s[28:29], s[28:29], s[26:27]
	s_and_b64 s[30:31], s[30:31], s[26:27]
	v_lshl_or_b32 v93, v93, 14, v94
	s_nop 1
	v_cndmask_b32_e64 v176, v176, 0, s[28:29]
	v_cndmask_b32_e64 v124, -1, v93, s[30:31]
	v_cmp_eq_u32_e64 s[26:27], s20, v177
	v_cmp_gt_u32_e64 s[28:29], s14, v126
	v_cmp_eq_u32_e64 s[30:31], s14, v126
	v_subrev_u32_e32 v93, s13, v112
	v_sub_u32_e32 v94, 0x3fff, v146
	s_and_b64 s[28:29], s[28:29], s[26:27]
	s_and_b64 s[30:31], s[30:31], s[26:27]
	v_lshl_or_b32 v93, v93, 14, v94
	s_nop 1
	v_cndmask_b32_e64 v177, v177, 0, s[28:29]
	v_cndmask_b32_e64 v126, -1, v93, s[30:31]
	v_cmp_eq_u32_e64 s[26:27], s20, v178
	v_cmp_gt_u32_e64 s[28:29], s14, v128
	v_cmp_eq_u32_e64 s[30:31], s14, v128
	v_subrev_u32_e32 v93, s13, v113
	v_sub_u32_e32 v94, 0x3fff, v148
	s_and_b64 s[28:29], s[28:29], s[26:27]
	s_and_b64 s[30:31], s[30:31], s[26:27]
	v_lshl_or_b32 v93, v93, 14, v94
	s_nop 1
	v_cndmask_b32_e64 v178, v178, 0, s[28:29]
	v_cndmask_b32_e64 v128, -1, v93, s[30:31]
	v_cmp_eq_u32_e64 s[26:27], s20, v179
	v_cmp_gt_u32_e64 s[28:29], s14, v129
	v_cmp_eq_u32_e64 s[30:31], s14, v129
	v_subrev_u32_e32 v93, s13, v114
	v_sub_u32_e32 v94, 0x3fff, v149
	s_and_b64 s[28:29], s[28:29], s[26:27]
	s_and_b64 s[30:31], s[30:31], s[26:27]
	v_lshl_or_b32 v93, v93, 14, v94
	s_nop 1
	v_cndmask_b32_e64 v179, v179, 0, s[28:29]
	v_cndmask_b32_e64 v129, -1, v93, s[30:31]
	v_cmp_eq_u32_e64 s[26:27], s20, v180
	v_cmp_gt_u32_e64 s[28:29], s14, v130
	v_cmp_eq_u32_e64 s[30:31], s14, v130
	v_subrev_u32_e32 v93, s13, v115
	v_sub_u32_e32 v94, 0x3fff, v150
	s_and_b64 s[28:29], s[28:29], s[26:27]
	s_and_b64 s[30:31], s[30:31], s[26:27]
	v_lshl_or_b32 v93, v93, 14, v94
	s_nop 1
	v_cndmask_b32_e64 v180, v180, 0, s[28:29]
	v_cndmask_b32_e64 v130, -1, v93, s[30:31]
	v_cmp_eq_u32_e64 s[26:27], s20, v181
	v_cmp_gt_u32_e64 s[28:29], s14, v131
	v_cmp_eq_u32_e64 s[30:31], s14, v131
	v_subrev_u32_e32 v93, s13, v116
	v_sub_u32_e32 v94, 0x3fff, v152
	s_and_b64 s[28:29], s[28:29], s[26:27]
	s_and_b64 s[30:31], s[30:31], s[26:27]
	v_lshl_or_b32 v93, v93, 14, v94
	s_nop 1
	v_cndmask_b32_e64 v181, v181, 0, s[28:29]
	v_cndmask_b32_e64 v131, -1, v93, s[30:31]
	v_cmp_eq_u32_e64 s[26:27], s20, v182
	v_cmp_gt_u32_e64 s[28:29], s14, v132
	v_cmp_eq_u32_e64 s[30:31], s14, v132
	v_subrev_u32_e32 v93, s13, v117
	v_sub_u32_e32 v94, 0x3fff, v153
	s_and_b64 s[28:29], s[28:29], s[26:27]
	s_and_b64 s[30:31], s[30:31], s[26:27]
	v_lshl_or_b32 v93, v93, 14, v94
	s_nop 1
	v_cndmask_b32_e64 v182, v182, 0, s[28:29]
	v_cndmask_b32_e64 v132, -1, v93, s[30:31]
	v_cmp_eq_u32_e64 s[26:27], s20, v183
	v_cmp_gt_u32_e64 s[28:29], s14, v134
	v_cmp_eq_u32_e64 s[30:31], s14, v134
	v_subrev_u32_e32 v93, s13, v118
	v_sub_u32_e32 v94, 0x3fff, v159
	s_and_b64 s[28:29], s[28:29], s[26:27]
	s_and_b64 s[30:31], s[30:31], s[26:27]
	v_lshl_or_b32 v93, v93, 14, v94
	s_nop 1
	v_cndmask_b32_e64 v183, v183, 0, s[28:29]
	v_cndmask_b32_e64 v134, -1, v93, s[30:31]
	v_cmp_eq_u32_e64 s[26:27], s20, v184
	v_cmp_gt_u32_e64 s[28:29], s14, v135
	v_cmp_eq_u32_e64 s[30:31], s14, v135
	v_subrev_u32_e32 v93, s13, v119
	v_sub_u32_e32 v94, 0x3fff, v160
	s_and_b64 s[28:29], s[28:29], s[26:27]
	s_and_b64 s[30:31], s[30:31], s[26:27]
	v_lshl_or_b32 v93, v93, 14, v94
	s_nop 1
	v_cndmask_b32_e64 v184, v184, 0, s[28:29]
	v_cndmask_b32_e64 v135, -1, v93, s[30:31]
	s_cmp_eq_u32 s25, 0
	s_cbranch_scc1 .Lfn_nodrop
	s_branch .Lfn_drop
.Lfn_direct:
	v_cmp_eq_u32_e64 s[26:27], s20, v173
	v_subrev_u32_e32 v93, s13, v108
	v_sub_u32_e32 v94, 0x3fff, v142
	v_lshl_or_b32 v93, v93, 14, v94
	v_cndmask_b32_e64 v120, -1, v93, s[26:27]
	v_cmp_eq_u32_e64 s[28:29], s20, v174
	v_subrev_u32_e32 v93, s13, v109
	v_sub_u32_e32 v94, 0x3fff, v143
	v_lshl_or_b32 v93, v93, 14, v94
	v_cndmask_b32_e64 v122, -1, v93, s[28:29]
	v_cmp_eq_u32_e64 s[30:31], s20, v175
	v_subrev_u32_e32 v93, s13, v110
	v_sub_u32_e32 v94, 0x3fff, v144
	v_lshl_or_b32 v93, v93, 14, v94
	v_cndmask_b32_e64 v123, -1, v93, s[30:31]
	v_cmp_eq_u32_e64 s[26:27], s20, v176
	v_subrev_u32_e32 v93, s13, v111
	v_sub_u32_e32 v94, 0x3fff, v145
	v_lshl_or_b32 v93, v93, 14, v94
	v_cndmask_b32_e64 v124, -1, v93, s[26:27]
	v_cmp_eq_u32_e64 s[28:29], s20, v177
	v_subrev_u32_e32 v93, s13, v112
	v_sub_u32_e32 v94, 0x3fff, v146
	v_lshl_or_b32 v93, v93, 14, v94
	v_cndmask_b32_e64 v126, -1, v93, s[28:29]
	v_cmp_eq_u32_e64 s[30:31], s20, v178
	v_subrev_u32_e32 v93, s13, v113
	v_sub_u32_e32 v94, 0x3fff, v148
	v_lshl_or_b32 v93, v93, 14, v94
	v_cndmask_b32_e64 v128, -1, v93, s[30:31]
	v_cmp_eq_u32_e64 s[26:27], s20, v179
	v_subrev_u32_e32 v93, s13, v114
	v_sub_u32_e32 v94, 0x3fff, v149
	v_lshl_or_b32 v93, v93, 14, v94
	v_cndmask_b32_e64 v129, -1, v93, s[26:27]
	v_cmp_eq_u32_e64 s[28:29], s20, v180
	v_subrev_u32_e32 v93, s13, v115
	v_sub_u32_e32 v94, 0x3fff, v150
	v_lshl_or_b32 v93, v93, 14, v94
	v_cndmask_b32_e64 v130, -1, v93, s[28:29]
	v_cmp_eq_u32_e64 s[30:31], s20, v181
	v_subrev_u32_e32 v93, s13, v116
	v_sub_u32_e32 v94, 0x3fff, v152
	v_lshl_or_b32 v93, v93, 14, v94
	v_cndmask_b32_e64 v131, -1, v93, s[30:31]
	v_cmp_eq_u32_e64 s[26:27], s20, v182
	v_subrev_u32_e32 v93, s13, v117
	v_sub_u32_e32 v94, 0x3fff, v153
	v_lshl_or_b32 v93, v93, 14, v94
	v_cndmask_b32_e64 v132, -1, v93, s[26:27]
	v_cmp_eq_u32_e64 s[28:29], s20, v183
	v_subrev_u32_e32 v93, s13, v118
	v_sub_u32_e32 v94, 0x3fff, v159
	v_lshl_or_b32 v93, v93, 14, v94
	v_cndmask_b32_e64 v134, -1, v93, s[28:29]
	v_cmp_eq_u32_e64 s[30:31], s20, v184
	v_subrev_u32_e32 v93, s13, v119
	v_sub_u32_e32 v94, 0x3fff, v160
	v_lshl_or_b32 v93, v93, 14, v94
	v_cndmask_b32_e64 v135, -1, v93, s[30:31]
.Lfn_drop:
	v_min3_u32 v92, v120, v122, v123
	v_min3_u32 v92, v124, v126, v92
	v_min3_u32 v92, v128, v129, v92
	v_min3_u32 v92, v130, v131, v92
	v_min3_u32 v92, v132, v134, v92
	v_min_u32_e32 v92, v135, v92
	s_nop 1
	v_min_u32_dpp v92, v92, v92 quad_perm:[1,0,3,2] row_mask:0xf bank_mask:0xf bound_ctrl:1
	s_nop 1
	v_min_u32_dpp v92, v92, v92 quad_perm:[2,3,0,1] row_mask:0xf bank_mask:0xf bound_ctrl:1
	s_nop 1
	v_min_u32_dpp v92, v92, v92 row_half_mirror row_mask:0xf bank_mask:0xf bound_ctrl:1
	s_nop 1
	v_min_u32_dpp v92, v92, v92 row_mirror row_mask:0xf bank_mask:0xf bound_ctrl:1
	s_nop 1
	v_readlane_b32 s16, v92, 0
	v_readlane_b32 s17, v92, 16
	v_readlane_b32 s18, v92, 32
	v_readlane_b32 s19, v92, 48
	s_min_u32 s16, s16, s17
	s_min_u32 s18, s18, s19
	s_min_u32 s16, s16, s18
	s_nop 0
	v_cmp_eq_u32_e64 s[26:27], s16, v120
	v_cmp_eq_u32_e64 s[28:29], s16, v122
	v_cmp_eq_u32_e64 s[30:31], s16, v123
	v_cndmask_b32_e64 v120, v120, -1, s[26:27]
	v_cndmask_b32_e64 v173, v173, 0, s[26:27]
	v_cmp_eq_u32_e64 s[26:27], s16, v124
	v_cndmask_b32_e64 v122, v122, -1, s[28:29]
	v_cndmask_b32_e64 v174, v174, 0, s[28:29]
	v_cmp_eq_u32_e64 s[28:29], s16, v126
	v_cndmask_b32_e64 v123, v123, -1, s[30:31]
	v_cndmask_b32_e64 v175, v175, 0, s[30:31]
	v_cmp_eq_u32_e64 s[30:31], s16, v128
	v_cndmask_b32_e64 v124, v124, -1, s[26:27]
	v_cndmask_b32_e64 v176, v176, 0, s[26:27]
	v_cmp_eq_u32_e64 s[26:27], s16, v129
	v_cndmask_b32_e64 v126, v126, -1, s[28:29]
	v_cndmask_b32_e64 v177, v177, 0, s[28:29]
	v_cmp_eq_u32_e64 s[28:29], s16, v130
	v_cndmask_b32_e64 v128, v128, -1, s[30:31]
	v_cndmask_b32_e64 v178, v178, 0, s[30:31]
	v_cmp_eq_u32_e64 s[30:31], s16, v131
	v_cndmask_b32_e64 v129, v129, -1, s[26:27]
	v_cndmask_b32_e64 v179, v179, 0, s[26:27]
	v_cmp_eq_u32_e64 s[26:27], s16, v132
	v_cndmask_b32_e64 v130, v130, -1, s[28:29]
	v_cndmask_b32_e64 v180, v180, 0, s[28:29]
	v_cmp_eq_u32_e64 s[28:29], s16, v134
	v_cndmask_b32_e64 v131, v131, -1, s[30:31]
	v_cndmask_b32_e64 v181, v181, 0, s[30:31]
	v_cmp_eq_u32_e64 s[30:31], s16, v135
	v_cndmask_b32_e64 v132, v132, -1, s[26:27]
	v_cndmask_b32_e64 v182, v182, 0, s[26:27]
	s_nop 0
	v_cndmask_b32_e64 v134, v134, -1, s[28:29]
	v_cndmask_b32_e64 v183, v183, 0, s[28:29]
	v_cndmask_b32_e64 v135, v135, -1, s[30:31]
	v_cndmask_b32_e64 v184, v184, 0, s[30:31]
	s_add_i32 s25, s25, -1
	s_cmp_lg_u32 s25, 0
	s_cbranch_scc1 .Lfn_drop
.Lfn_nodrop:
	s_movk_i32 s19, 0x100
	v_mov_b32_e32 v120, 0
	v_cmp_le_u32_e64 s[26:27], s20, v173
	v_cmp_le_u32_e64 s[28:29], s20, v174
	v_cmp_le_u32_e64 s[30:31], s20, v175
	v_addc_co_u32_e64 v120, vcc, 0, v120, s[26:27]
	v_cmp_le_u32_e64 s[26:27], s20, v176
	v_addc_co_u32_e64 v120, vcc, 0, v120, s[28:29]
	v_cmp_le_u32_e64 s[28:29], s20, v177
	v_addc_co_u32_e64 v120, vcc, 0, v120, s[30:31]
	v_cmp_le_u32_e64 s[30:31], s20, v178
	v_addc_co_u32_e64 v120, vcc, 0, v120, s[26:27]
	v_cmp_le_u32_e64 s[26:27], s20, v179
	v_addc_co_u32_e64 v120, vcc, 0, v120, s[28:29]
	v_cmp_le_u32_e64 s[28:29], s20, v180
	v_addc_co_u32_e64 v120, vcc, 0, v120, s[30:31]
	v_cmp_le_u32_e64 s[30:31], s20, v181
	v_addc_co_u32_e64 v120, vcc, 0, v120, s[26:27]
	v_cmp_le_u32_e64 s[26:27], s20, v182
	v_addc_co_u32_e64 v120, vcc, 0, v120, s[28:29]
	v_cmp_le_u32_e64 s[28:29], s20, v183
	v_addc_co_u32_e64 v120, vcc, 0, v120, s[30:31]
	v_cmp_le_u32_e64 s[30:31], s20, v184
	v_addc_co_u32_e64 v120, vcc, 0, v120, s[26:27]
	s_nop 0
	v_addc_co_u32_e64 v120, vcc, 0, v120, s[28:29]
	v_addc_co_u32_e64 v120, vcc, 0, v120, s[30:31]
	v_mov_b32_e32 v122, v120
	s_nop 1
	v_add_u32_dpp v122, v122, v122 row_shr:1 row_mask:0xf bank_mask:0xf bound_ctrl:1
	s_nop 1
	v_add_u32_dpp v122, v122, v122 row_shr:2 row_mask:0xf bank_mask:0xf bound_ctrl:1
	s_nop 1
	v_add_u32_dpp v122, v122, v122 row_shr:4 row_mask:0xf bank_mask:0xf bound_ctrl:1
	s_nop 1
	v_add_u32_dpp v122, v122, v122 row_shr:8 row_mask:0xf bank_mask:0xf bound_ctrl:1
	s_nop 1
	v_add_u32_dpp v122, v122, v122 row_bcast:15 row_mask:0xa bank_mask:0xf
	s_nop 1
	v_add_u32_dpp v122, v122, v122 row_bcast:31 row_mask:0xc bank_mask:0xf
	s_nop 1
	v_sub_u32_e32 v122, v122, v120
	s_mov_b64 s[22:23], exec
	v_cmp_le_u32_e64 s[26:27], s20, v173
	s_mov_b64 exec, s[26:27]
	s_cbranch_execz .Lfn_w0
	v_lshl_add_u32 v93, v122, 2, s9
	v_lshl_add_u32 v94, v122, 1, s10
	ds_write_b32 v93, v161
	ds_write_b16 v94, v142
	v_add_u32_e32 v122, 1, v122

.Lfn_w11:
	s_mov_b64 exec, s[22:23]
	s_mov_b64 exec, s[58:59]
	v_mov_b32_e32 v40, s11
	v_mov_b32_e32 v92, s19
	ds_write_b32 v40, v92
	s_mov_b64 exec, s[22:23]
	v_mov_b32_e32 v143, s24
	s_branch .LBB0_222
.Lfn_orig:
	v_mov_b32_e32 v143, s24
	s_movk_i32 s4, 0x300
	v_mul_lo_u32 v9, v9, s4
	v_lshl_add_u32 v27, v9, 2, 0
	v_lshl_add_u32 v10, v190, 2, v27
	ds_read2st64_b32 v[10:11], v10 offset1:1
	s_add_i32 s4, 0, 0x18000
	v_lshl_add_u32 v33, v9, 1, s4
	v_cmp_lt_u32_e64 s[4:5], v0, v8
	v_lshl_add_u32 v9, v190, 1, v33
	s_waitcnt lgkmcnt(0)
	v_not_b32_e32 v12, v10
	v_cmp_gt_i32_e32 vcc, 0, v10
	v_lshl_add_u32 v14, v192, 1, v33
	v_lshl_add_u32 v16, v191, 2, v27
	v_cndmask_b32_e64 v40, -|v10|, v12, vcc
	v_lshl_add_u32 v10, v192, 2, v27
	v_lshl_add_u32 v17, v191, 1, v33
	v_cndmask_b32_e64 v18, 0, v0, s[4:5]
	v_lshl_add_u32 v19, v18, 2, v27
	v_lshl_add_u32 v18, v18, 1, v33
	ds_read_u16 v20, v9
	ds_read_u16 v9, v9 offset:128
	ds_read_b32 v10, v10
	ds_read_u16 v14, v14
	ds_read_b32 v16, v16
	ds_read_u16 v17, v17
	ds_read_b32 v22, v19
	ds_read_u16 v24, v18
	s_waitcnt lgkmcnt(7)
	v_sub_co_u32_sdwa v53, vcc, s66, v20 dst_sel:DWORD dst_unused:UNUSED_PAD src0_sel:DWORD src1_sel:WORD_0
	s_waitcnt lgkmcnt(6)
	v_and_b32_e32 v9, 0xffff, v9
	v_not_b32_e32 v18, v11
	v_cmp_gt_i32_e32 vcc, 0, v11
	v_lshlrev_b64 v[12:13], 14, v[40:41]
	v_mov_b32_e32 v56, 0x3fff
	v_cndmask_b32_e64 v40, -|v11|, v18, vcc
	v_sub_co_u32_e32 v49, vcc, s66, v9
	s_waitcnt lgkmcnt(4)
	v_and_b32_e32 v9, 0xffff, v14
	v_not_b32_e32 v11, v10
	v_cmp_gt_i32_e32 vcc, 0, v10
	v_lshlrev_b64 v[28:29], 14, v[40:41]
	v_cmp_lt_u32_e64 s[6:7], v1, v8
	v_cndmask_b32_e64 v40, -|v10|, v11, vcc
	v_sub_co_u32_e32 v45, vcc, s66, v9
	s_waitcnt lgkmcnt(2)
	v_and_b32_e32 v9, 0xffff, v17
	v_not_b32_e32 v10, v16
	v_cmp_gt_i32_e32 vcc, 0, v16
	v_lshlrev_b64 v[20:21], 14, v[40:41]
	v_cmp_lt_u32_e64 s[8:9], v2, v8
	v_cndmask_b32_e64 v40, -|v16|, v10, vcc
	v_sub_co_u32_e32 v37, vcc, s66, v9
	s_waitcnt lgkmcnt(1)
	v_cndmask_b32_e64 v9, 0, v22, s[4:5]
	v_not_b32_e32 v10, v9
	v_cmp_gt_i32_e32 vcc, 0, v9
	v_lshlrev_b64 v[18:19], 14, v[40:41]
	v_cmp_lt_u32_e64 s[10:11], v3, v8
	v_cndmask_b32_e64 v40, -|v9|, v10, vcc
	s_waitcnt lgkmcnt(0)
	v_sub_u32_e32 v9, 0x3fff, v24
	v_cndmask_b32_e64 v14, v56, v9, s[4:5]
	v_cndmask_b32_e64 v9, 0, v1, s[6:7]
	v_cndmask_b32_e64 v11, 0, v2, s[8:9]
	v_cndmask_b32_e64 v24, 0, v3, s[10:11]
	v_cmp_lt_u32_e64 s[12:13], v6, v8
	v_lshl_add_u32 v10, v9, 2, v27
	v_lshl_add_u32 v9, v9, 1, v33
	v_lshl_add_u32 v22, v11, 2, v27
	v_lshl_add_u32 v11, v11, 1, v33
	v_lshl_add_u32 v25, v24, 2, v27
	v_lshl_add_u32 v24, v24, 1, v33
	v_cndmask_b32_e64 v26, 0, v6, s[12:13]
	v_lshl_add_u32 v30, v26, 2, v27
	v_lshl_add_u32 v26, v26, 1, v33
	ds_read_b32 v10, v10
	ds_read_u16 v9, v9
	ds_read_b32 v22, v22
	ds_read_u16 v11, v11
	ds_read_b32 v25, v25
	ds_read_u16 v24, v24
	ds_read_b32 v32, v30
	ds_read_u16 v34, v26
	s_waitcnt lgkmcnt(7)
	v_cndmask_b32_e64 v10, 0, v10, s[6:7]
	s_waitcnt lgkmcnt(6)
	v_sub_u32_e32 v9, 0x3fff, v9
	v_not_b32_e32 v26, v10
	v_cmp_gt_i32_e32 vcc, 0, v10
	v_cndmask_b32_e64 v48, v56, v9, s[6:7]
	s_waitcnt lgkmcnt(5)
	v_cndmask_b32_e64 v9, 0, v22, s[8:9]
	v_lshlrev_b64 v[16:17], 14, v[40:41]
	v_cndmask_b32_e64 v40, -|v10|, v26, vcc
	v_not_b32_e32 v10, v9
	v_cmp_gt_i32_e32 vcc, 0, v9
	v_lshlrev_b64 v[50:51], 14, v[40:41]
	v_cmp_lt_u32_e64 s[14:15], v7, v8
	v_cndmask_b32_e64 v40, -|v9|, v10, vcc
	s_waitcnt lgkmcnt(4)
	v_sub_u32_e32 v9, 0x3fff, v11
	v_cndmask_b32_e64 v36, v56, v9, s[8:9]
	s_waitcnt lgkmcnt(3)
	v_cndmask_b32_e64 v9, 0, v25, s[10:11]
	v_not_b32_e32 v10, v9
	v_cmp_gt_i32_e32 vcc, 0, v9
	v_lshlrev_b64 v[38:39], 14, v[40:41]
	v_cmp_lt_u32_e64 s[16:17], v4, v8
	v_cndmask_b32_e64 v40, -|v9|, v10, vcc
	s_waitcnt lgkmcnt(2)
	v_sub_u32_e32 v9, 0x3fff, v24
	v_cndmask_b32_e64 v26, v56, v9, s[10:11]
	s_waitcnt lgkmcnt(1)
	v_cndmask_b32_e64 v9, 0, v32, s[12:13]
	v_not_b32_e32 v10, v9
	v_cmp_gt_i32_e32 vcc, 0, v9
	v_lshlrev_b64 v[30:31], 14, v[40:41]
	v_cmp_lt_u32_e64 s[18:19], v5, v8
	v_cndmask_b32_e64 v40, -|v9|, v10, vcc
	s_waitcnt lgkmcnt(0)
	v_sub_u32_e32 v9, 0x3fff, v34
	v_cndmask_b32_e64 v22, v56, v9, s[12:13]
	v_cndmask_b32_e64 v9, 0, v7, s[14:15]
	v_cndmask_b32_e64 v11, 0, v4, s[16:17]
	v_cndmask_b32_e64 v8, 0, v5, s[18:19]
	v_lshl_add_u32 v10, v9, 2, v27
	v_lshl_add_u32 v9, v9, 1, v33
	v_lshl_add_u32 v32, v11, 2, v27
	v_lshl_add_u32 v11, v11, 1, v33
	v_lshl_add_u32 v34, v8, 2, v27
	v_lshl_add_u32 v8, v8, 1, v33
	ds_read_b32 v10, v10
	ds_read_u16 v9, v9
	ds_read_b32 v32, v32
	ds_read_u16 v11, v11
	ds_read_b32 v34, v34
	ds_read_u16 v8, v8
	s_waitcnt lgkmcnt(5)
	v_cndmask_b32_e64 v10, 0, v10, s[14:15]
	s_waitcnt lgkmcnt(4)
	v_sub_u32_e32 v9, 0x3fff, v9
	v_not_b32_e32 v35, v10
	v_cmp_gt_i32_e32 vcc, 0, v10
	v_cndmask_b32_e64 v52, v56, v9, s[14:15]
	s_waitcnt lgkmcnt(3)
	v_cndmask_b32_e64 v9, 0, v32, s[16:17]
	v_lshlrev_b64 v[24:25], 14, v[40:41]
	v_cndmask_b32_e64 v40, -|v10|, v35, vcc
	v_not_b32_e32 v10, v9
	v_cmp_gt_i32_e32 vcc, 0, v9
	v_lshlrev_b64 v[54:55], 14, v[40:41]
	v_or_b32_e32 v12, v12, v53
	v_cndmask_b32_e64 v40, -|v9|, v10, vcc
	s_waitcnt lgkmcnt(2)
	v_sub_u32_e32 v9, 0x3fff, v11
	v_cndmask_b32_e64 v44, v56, v9, s[16:17]
	s_waitcnt lgkmcnt(1)
	v_cndmask_b32_e64 v9, 0, v34, s[18:19]
	v_or_b32_e32 v28, v28, v49
	v_not_b32_e32 v10, v9
	v_cmp_gt_i32_e32 vcc, 0, v9
	v_readfirstlane_b32 s21, v12
	v_or_b32_e32 v20, v20, v45
	v_or_b32_e32 v18, v18, v37
	v_lshlrev_b64 v[46:47], 14, v[40:41]
	v_cndmask_b32_e64 v40, -|v9|, v10, vcc
	s_waitcnt lgkmcnt(0)
	v_sub_u32_e32 v8, 0x3fff, v8
	v_xor_b32_e32 v9, s21, v12
	v_xor_b32_e32 v11, s21, v28
	v_or_b32_e32 v16, v16, v14
	v_or_b32_e32 v50, v50, v48
	v_cndmask_b32_e64 v32, v56, v8, s[18:19]
	v_or_b32_e32 v9, v11, v9
	v_xor_b32_e32 v11, s21, v20
	v_xor_b32_e32 v56, s21, v18
	v_or3_b32 v9, v9, v11, v56
	v_xor_b32_e32 v11, s21, v16
	v_xor_b32_e32 v56, s21, v50
	v_or_b32_e32 v38, v38, v36
	v_or_b32_e32 v30, v30, v26
	v_cndmask_b32_e64 v11, 0, v11, s[4:5]
	v_cndmask_b32_e64 v56, 0, v56, s[6:7]
	v_or3_b32 v9, v9, v11, v56
	v_xor_b32_e32 v11, s21, v38
	v_xor_b32_e32 v56, s21, v30
	v_or_b32_e32 v24, v24, v22
	v_or_b32_e32 v54, v54, v52
	v_readfirstlane_b32 s20, v13
	v_cndmask_b32_e64 v11, 0, v11, s[8:9]
	v_cndmask_b32_e64 v56, 0, v56, s[10:11]
	v_lshlrev_b64 v[34:35], 14, v[40:41]
	v_xor_b32_e32 v8, s20, v13
	v_xor_b32_e32 v10, s20, v29
	v_or3_b32 v9, v9, v11, v56
	v_xor_b32_e32 v11, s21, v24
	v_xor_b32_e32 v56, s21, v54
	v_or_b32_e32 v46, v46, v44
	v_or_b32_e32 v34, v34, v32
	v_or_b32_e32 v8, v10, v8
	v_xor_b32_e32 v10, s20, v21
	v_xor_b32_e32 v40, s20, v19
	v_cndmask_b32_e64 v11, 0, v11, s[12:13]
	v_cndmask_b32_e64 v56, 0, v56, s[14:15]
	v_or3_b32 v8, v8, v10, v40
	v_xor_b32_e32 v10, s20, v17
	v_xor_b32_e32 v40, s20, v51
	v_or3_b32 v9, v9, v11, v56
	v_xor_b32_e32 v11, s21, v46
	v_xor_b32_e32 v56, s21, v34
	v_cndmask_b32_e64 v10, 0, v10, s[4:5]
	v_cndmask_b32_e64 v40, 0, v40, s[6:7]
	v_cndmask_b32_e64 v11, 0, v11, s[16:17]
	v_cndmask_b32_e64 v56, 0, v56, s[18:19]
	v_or3_b32 v8, v8, v10, v40
	v_xor_b32_e32 v10, s20, v39
	v_xor_b32_e32 v40, s20, v31
	v_or3_b32 v9, v9, v11, v56
	v_cndmask_b32_e64 v10, 0, v10, s[8:9]
	v_cndmask_b32_e64 v40, 0, v40, s[10:11]
	v_or_b32_dpp v9, v9, v9 quad_perm:[1,0,3,2] row_mask:0xf bank_mask:0xf bound_ctrl:1
	v_or3_b32 v8, v8, v10, v40
	v_xor_b32_e32 v10, s20, v25
	v_xor_b32_e32 v40, s20, v55
	v_or_b32_dpp v9, v9, v9 quad_perm:[2,3,0,1] row_mask:0xf bank_mask:0xf bound_ctrl:1
	v_cndmask_b32_e64 v10, 0, v10, s[12:13]
	v_cndmask_b32_e64 v40, 0, v40, s[14:15]
	v_or_b32_dpp v9, v9, v9 row_half_mirror row_mask:0xf bank_mask:0xf bound_ctrl:1
	v_or3_b32 v8, v8, v10, v40
	v_xor_b32_e32 v10, s20, v47
	v_xor_b32_e32 v40, s20, v35
	v_or_b32_dpp v9, v9, v9 row_mirror row_mask:0xf bank_mask:0xf bound_ctrl:1
	v_cndmask_b32_e64 v10, 0, v10, s[16:17]
	v_cndmask_b32_e64 v40, 0, v40, s[18:19]
	v_readlane_b32 s20, v9, 0
	v_readlane_b32 s21, v9, 16
	v_or3_b32 v10, v8, v10, v40
	s_or_b32 s20, s21, s20
	v_readlane_b32 s21, v9, 32
	s_or_b32 s20, s20, s21
	v_readlane_b32 s21, v9, 48
	v_or_b32_dpp v9, v10, v10 quad_perm:[1,0,3,2] row_mask:0xf bank_mask:0xf bound_ctrl:1
	v_cndmask_b32_e64 v8, 0, 1, s[10:11]
	s_or_b32 s20, s20, s21
	v_or_b32_dpp v9, v9, v9 quad_perm:[2,3,0,1] row_mask:0xf bank_mask:0xf bound_ctrl:1
	v_lshlrev_b16_e32 v11, 8, v8
	v_cndmask_b32_e64 v8, 0, 1, s[6:7]
	v_or_b32_dpp v9, v9, v9 row_half_mirror row_mask:0xf bank_mask:0xf bound_ctrl:1
	v_lshlrev_b16_e32 v8, 8, v8
	v_mov_b32_e32 v40, 8
	v_or_b32_dpp v9, v9, v9 row_mirror row_mask:0xf bank_mask:0xf bound_ctrl:1
	v_lshrrev_b32_sdwa v40, v40, v8 dst_sel:BYTE_1 dst_unused:UNUSED_PAD src0_sel:DWORD src1_sel:DWORD
	v_readlane_b32 s21, v9, 0
	v_readlane_b32 s22, v9, 16
	s_or_b32 s21, s22, s21
	v_readlane_b32 s22, v9, 32
	s_or_b32 s21, s21, s22
	v_readlane_b32 s22, v9, 48
	v_cndmask_b32_e64 v8, 0, 1, s[14:15]
	s_or_b32 s21, s21, s22
	v_lshlrev_b16_e32 v8, 8, v8
	v_cndmask_b32_e64 v56, 0, 1, s[12:13]
	s_flbit_i32_b64 s22, s[20:21]
	v_or_b32_e32 v8, v56, v8
	v_cndmask_b32_e64 v56, 0, 1, s[18:19]
	s_sub_i32 s22, 56, s22
	v_cndmask_b32_e64 v10, 0, 1, s[4:5]
	v_lshlrev_b16_e32 v56, 8, v56
	v_cndmask_b32_e64 v57, 0, 1, s[16:17]
	s_max_i32 s22, s22, 0
	v_or_b32_e32 v10, v10, v40
	v_cndmask_b32_e64 v40, 0, 1, s[8:9]
	v_or_b32_sdwa v56, v57, v56 dst_sel:WORD_1 dst_unused:UNUSED_PAD src0_sel:DWORD src1_sel:DWORD
	s_cmp_lg_u64 s[20:21], 0
	v_or_b32_sdwa v11, v40, v11 dst_sel:WORD_1 dst_unused:UNUSED_PAD src0_sel:DWORD src1_sel:DWORD
	v_or_b32_sdwa v8, v8, v56 dst_sel:DWORD dst_unused:UNUSED_PAD src0_sel:WORD_0 src1_sel:DWORD
	s_cselect_b32 s56, s22, 0
	v_mov_b32_e32 v9, 0x1010101
	v_or_b32_sdwa v10, v10, v11 dst_sel:DWORD dst_unused:UNUSED_PAD src0_sel:WORD_0 src1_sel:DWORD
	s_movk_i32 s55, 0x100
	v_mov_b32_e32 v40, 8
	s_branch .LBB0_226
